# v47 + P3 sigmoid epilogue: adjacent scale-multiply and +1.0 pairs as packed v_pk_mul_f32 / v_pk_add_f32
# baseline (speedup 1.0000x reference)
; #define LAS __attribute__((address_space(3)))
; __device__ __forceinline__ unsigned xb_add(unsigned* p, unsigned v) { return __hip_atomic_fetch_add(p, v, __ATOMIC_RELAXED, __HIP_MEMORY_SCOPE_AGENT); }
; __device__ __forceinline__ unsigned xb_xcc_id() { return (unsigned)__builtin_amdgcn_s_getreg((3 << 11) | 20) & 0xFu; }
; __global__ void __launch_bounds__(512, 2) fwd_megakernel(Args args) {
;     extern __shared__ __attribute__((aligned(16))) unsigned char lds_raw[];
;     LAS unsigned char* lds = (LAS unsigned char*)lds_raw;
;     cg::grid_group grid = cg::this_grid();
;     const int wave = __builtin_amdgcn_readfirstlane(threadIdx.x >> 6);
;     const int G = gridDim.x, bx = blockIdx.x;
;     XcdBarrier xbar; xbar.bar = (unsigned*)(args.ws + 32768); xbar.x = xb_xcc_id(); xbar.st = (volatile LAS unsigned*)(lds + 138240);
;     if (threadIdx.x == 0) { xbar.st[0] = 0u; xbar.st[1] = 0u; (void)xb_add(&xbar.bar[XB_XCNT(xbar.x)], 1u); }
_Z14fwd_megakernel4Args:
	s_mov_b32 s98, 0xbd38aa3b
	s_mov_b32 s99, 0
	s_mov_b32 s100, 1.0
	s_mov_b32 s101, 0
	s_load_dwordx8 s[52:59], s[0:1], 0x80
	s_add_u32 s10, s0, 0xa0
	s_addc_u32 s11, s1, 0
	s_load_dword s28, s[0:1], 0xa0
	v_and_b32_e32 v86, 0x3ff, v0
	s_waitcnt lgkmcnt(0)
	s_add_u32 s4, s58, 0x8000
	s_addc_u32 s5, s59, 0
	v_writelane_b32 v249, s4, 0
	s_getreg_b32 s3, hwreg(HW_REG_XCC_ID, 0, 4)
	v_readfirstlane_b32 s60, v86
	v_writelane_b32 v249, s5, 1
	s_and_b32 s3, s3, 15
	v_cmp_eq_u32_e32 vcc, 0, v86
	v_writelane_b32 v249, s3, 2
	s_and_saveexec_b64 s[4:5], vcc
	s_cbranch_execz .LBB0_3
	s_add_i32 s3, 0, 0x21c00
	v_mov_b32_e32 v1, 0
	v_mov_b32_e32 v2, s3
	s_add_i32 s3, 0, 0x21c04
	s_mov_b64 s[6:7], exec
	ds_write_b32 v2, v1
	v_mov_b32_e32 v2, s3
	ds_write_b32 v2, v1
	v_mbcnt_lo_u32_b32 v1, s6, 0
	v_mbcnt_hi_u32_b32 v1, s7, v1
	v_cmp_eq_u32_e32 vcc, 0, v1
	s_and_b64 s[8:9], exec, vcc
	s_mov_b64 exec, s[8:9]
	s_cbranch_execz .LBB0_3
	v_readlane_b32 s3, v249, 2
	s_bcnt1_i32_b64 s6, s[6:7]
	s_lshl_b32 s3, s3, 8
	v_mov_b32_e32 v2, s6
	v_readlane_b32 s6, v249, 0
	v_mov_b32_e32 v1, s3
	v_readlane_b32 s7, v249, 1
	s_nop 4
	global_atomic_add v1, v2, s[6:7] offset:1024

; __device__ __forceinline__ u32x2 pk4(f32x4 v) { u32x2 w; w.x = pk2(v[0], v[1]); w.y = pk2(v[2], v[3]); return w; }
;     __device__ __forceinline__ void operator()(const f32x4 (&acc)[2][2][4][2], const Unit& u, int wr, int wc, int fr, int fq) const {
;     ...
;         if (mode == 0) {
; #pragma unroll
;             for (int ai = 0; ai < 2; ++ai)
; #pragma unroll
;                 for (int bj = 0; bj < 2; ++bj)
; #pragma unroll
;                     for (int m = 0; m < 4; ++m)
; #pragma unroll
;                         for (int n = 0; n < 2; ++n) { const int idx = ((ai * 2 + bj) * 4 + m) * 2 + n; f32x4 a = acc[ai][bj][m][n], sg;
; #pragma unroll
;                             for (int e = 0; e < 4; ++e) sg[e] = __builtin_amdgcn_rcpf(1.0f + __builtin_amdgcn_exp2f((-1.4426950408889634f / 32.0f) * a[e]));
;                             tg[idx * 64] = pk4(sg); if (n) asm volatile("" ::: "memory"); }
.LBB0_670:
	v_pk_mul_f32 v[124:125], v[124:125], s[98:99] op_sel_hi:[1,0]
	v_exp_f32_e32 v124, v124
	v_exp_f32_e32 v125, v125
	v_mul_f32_e32 v120, 0xbd38aa3b, v120
	v_exp_f32_e32 v128, v120
	v_mul_f32_e32 v120, 0xbd38aa3b, v121
	v_pk_add_f32 v[124:125], v[124:125], s[100:101] op_sel_hi:[1,0]
	v_pk_mul_f32 v[126:127], v[126:127], s[98:99] op_sel_hi:[1,0]
	v_exp_f32_e32 v121, v120
	v_mul_f32_e32 v122, 0xbd38aa3b, v122
	v_rcp_f32_e32 v124, v124
	v_exp_f32_e32 v126, v126
	v_exp_f32_e32 v127, v127
	v_rcp_f32_e32 v125, v125
	v_exp_f32_e32 v122, v122
	v_mul_f32_e32 v123, 0xbd38aa3b, v123
	v_exp_f32_e32 v123, v123
	v_add_f32_e32 v121, 1.0, v121
	v_pk_add_f32 v[126:127], v[126:127], s[100:101] op_sel_hi:[1,0]
	v_cvt_pk_bf16_f32 v120, v124, v125
	v_rcp_f32_e32 v125, v121
	v_add_f32_e32 v121, 1.0, v122
	v_rcp_f32_e32 v126, v126
	v_rcp_f32_e32 v127, v127
	v_add_f32_e32 v124, 1.0, v128
	v_rcp_f32_e32 v122, v121
	v_add_f32_e32 v121, 1.0, v123
	v_rcp_f32_e32 v124, v124
	v_rcp_f32_e32 v123, v121
	v_pk_mul_f32 v[116:117], v[116:117], s[98:99] op_sel_hi:[1,0]
	v_exp_f32_e32 v116, v116
	v_exp_f32_e32 v117, v117
	v_cvt_pk_bf16_f32 v121, v126, v127
	flat_store_dwordx2 v[134:135], v[120:121]
	v_cvt_pk_bf16_f32 v120, v124, v125
	v_cvt_pk_bf16_f32 v121, v122, v123
	v_mul_f32_e32 v112, 0xbd38aa3b, v112
	flat_store_dwordx2 v[134:135], v[120:121] offset:512
	v_exp_f32_e32 v120, v112
	v_mul_f32_e32 v112, 0xbd38aa3b, v113
	v_pk_add_f32 v[116:117], v[116:117], s[100:101] op_sel_hi:[1,0]
	v_pk_mul_f32 v[118:119], v[118:119], s[98:99] op_sel_hi:[1,0]
	v_exp_f32_e32 v113, v112
	v_mul_f32_e32 v114, 0xbd38aa3b, v114
	v_rcp_f32_e32 v116, v116
	v_exp_f32_e32 v118, v118
	v_exp_f32_e32 v119, v119
	v_rcp_f32_e32 v117, v117
	v_exp_f32_e32 v114, v114
	v_mul_f32_e32 v115, 0xbd38aa3b, v115
	v_exp_f32_e32 v115, v115
	v_add_f32_e32 v113, 1.0, v113
	v_pk_add_f32 v[118:119], v[118:119], s[100:101] op_sel_hi:[1,0]
	v_cvt_pk_bf16_f32 v112, v116, v117
	v_rcp_f32_e32 v117, v113
	v_add_f32_e32 v113, 1.0, v114
	v_rcp_f32_e32 v118, v118
	v_rcp_f32_e32 v119, v119
	v_add_f32_e32 v116, 1.0, v120
	v_rcp_f32_e32 v114, v113
	v_add_f32_e32 v113, 1.0, v115
	v_rcp_f32_e32 v116, v116
	v_rcp_f32_e32 v115, v113
	v_pk_mul_f32 v[108:109], v[108:109], s[98:99] op_sel_hi:[1,0]
	v_exp_f32_e32 v108, v108
	v_exp_f32_e32 v109, v109
	v_cvt_pk_bf16_f32 v113, v118, v119
	flat_store_dwordx2 v[134:135], v[112:113] offset:1024
	v_cvt_pk_bf16_f32 v112, v116, v117
	v_cvt_pk_bf16_f32 v113, v114, v115
	v_mul_f32_e32 v104, 0xbd38aa3b, v104
	flat_store_dwordx2 v[134:135], v[112:113] offset:1536
	v_exp_f32_e32 v112, v104
	v_mul_f32_e32 v104, 0xbd38aa3b, v105
	v_pk_add_f32 v[108:109], v[108:109], s[100:101] op_sel_hi:[1,0]
	v_pk_mul_f32 v[110:111], v[110:111], s[98:99] op_sel_hi:[1,0]
	v_exp_f32_e32 v105, v104
	v_mul_f32_e32 v106, 0xbd38aa3b, v106
	v_rcp_f32_e32 v108, v108
	v_exp_f32_e32 v110, v110
	v_exp_f32_e32 v111, v111
	v_rcp_f32_e32 v109, v109
	v_exp_f32_e32 v106, v106
	v_mul_f32_e32 v107, 0xbd38aa3b, v107
	v_exp_f32_e32 v107, v107
	v_add_f32_e32 v105, 1.0, v105
	v_pk_add_f32 v[110:111], v[110:111], s[100:101] op_sel_hi:[1,0]
	v_cvt_pk_bf16_f32 v104, v108, v109
	v_rcp_f32_e32 v109, v105
	v_add_f32_e32 v105, 1.0, v106
	v_rcp_f32_e32 v110, v110
	v_rcp_f32_e32 v111, v111
	v_add_f32_e32 v108, 1.0, v112
	v_rcp_f32_e32 v106, v105
	v_add_f32_e32 v105, 1.0, v107
	v_rcp_f32_e32 v108, v108
	v_rcp_f32_e32 v107, v105
	v_pk_mul_f32 v[100:101], v[100:101], s[98:99] op_sel_hi:[1,0]
	v_pk_mul_f32 v[92:93], v[92:93], s[98:99] op_sel_hi:[1,0]
	v_pk_mul_f32 v[94:95], v[94:95], s[98:99] op_sel_hi:[1,0]
	v_exp_f32_e32 v100, v100
	v_exp_f32_e32 v101, v101
	v_exp_f32_e32 v92, v92
	v_exp_f32_e32 v93, v93
	v_exp_f32_e32 v94, v94
	v_exp_f32_e32 v95, v95
	v_cvt_pk_bf16_f32 v105, v110, v111
	flat_store_dwordx2 v[134:135], v[104:105] offset:2048
	v_cvt_pk_bf16_f32 v104, v108, v109
	v_cvt_pk_bf16_f32 v105, v106, v107
	v_mul_f32_e32 v96, 0xbd38aa3b, v96
	flat_store_dwordx2 v[134:135], v[104:105] offset:2560
	v_exp_f32_e32 v104, v96
	v_mul_f32_e32 v96, 0xbd38aa3b, v97
	v_mul_f32_e32 v88, 0xbd38aa3b, v88
	v_pk_add_f32 v[100:101], v[100:101], s[100:101] op_sel_hi:[1,0]
	v_pk_mul_f32 v[102:103], v[102:103], s[98:99] op_sel_hi:[1,0]
	v_exp_f32_e32 v97, v96
	v_mul_f32_e32 v98, 0xbd38aa3b, v98
	v_pk_add_f32 v[92:93], v[92:93], s[100:101] op_sel_hi:[1,0]
	v_pk_add_f32 v[94:95], v[94:95], s[100:101] op_sel_hi:[1,0]
	v_exp_f32_e32 v88, v88
	v_mul_f32_e32 v89, 0xbd38aa3b, v89
	v_rcp_f32_e32 v100, v100
	v_exp_f32_e32 v102, v102
	v_exp_f32_e32 v103, v103
	v_rcp_f32_e32 v101, v101
	v_exp_f32_e32 v98, v98
	v_mul_f32_e32 v99, 0xbd38aa3b, v99
	v_rcp_f32_e32 v92, v92
	v_rcp_f32_e32 v93, v93
	v_rcp_f32_e32 v94, v94
	v_rcp_f32_e32 v95, v95
	v_exp_f32_e32 v89, v89
	v_exp_f32_e32 v99, v99
	v_add_f32_e32 v97, 1.0, v97
	v_add_f32_e32 v88, 1.0, v88
	v_pk_add_f32 v[102:103], v[102:103], s[100:101] op_sel_hi:[1,0]
	v_cvt_pk_bf16_f32 v96, v100, v101
	v_rcp_f32_e32 v101, v97
	v_add_f32_e32 v97, 1.0, v98
	v_cvt_pk_bf16_f32 v92, v92, v93
	v_cvt_pk_bf16_f32 v93, v94, v95
	v_rcp_f32_e32 v94, v88
	v_add_f32_e32 v88, 1.0, v89
	v_mul_f32_e32 v89, 0xbd38aa3b, v90
	v_rcp_f32_e32 v102, v102
	v_rcp_f32_e32 v103, v103
	v_add_f32_e32 v100, 1.0, v104
	v_rcp_f32_e32 v98, v97
	v_add_f32_e32 v97, 1.0, v99
	v_exp_f32_e32 v89, v89
	v_mul_f32_e32 v90, 0xbd38aa3b, v91
	v_rcp_f32_e32 v100, v100
	v_rcp_f32_e32 v99, v97
	v_exp_f32_e32 v90, v90
	v_cvt_pk_bf16_f32 v97, v102, v103
	v_rcp_f32_e32 v91, v88
	v_add_f32_e32 v88, 1.0, v89
	flat_store_dwordx2 v[134:135], v[96:97] offset:3072
	v_cvt_pk_bf16_f32 v96, v100, v101
	v_cvt_pk_bf16_f32 v97, v98, v99
	v_rcp_f32_e32 v95, v88
	v_add_f32_e32 v88, 1.0, v90
; __device__ __forceinline__ u32x2 pk4(f32x4 v) { u32x2 w; w.x = pk2(v[0], v[1]); w.y = pk2(v[2], v[3]); return w; }
;     __device__ __forceinline__ void operator()(const f32x4 (&acc)[2][2][4][2], const Unit& u, int wr, int wc, int fr, int fq) const {
;     ...
;         if (mode == 0) {
; #pragma unroll
;             for (int ai = 0; ai < 2; ++ai)
; #pragma unroll
;                 for (int bj = 0; bj < 2; ++bj)
; #pragma unroll
;                     for (int m = 0; m < 4; ++m)
; #pragma unroll
;                         for (int n = 0; n < 2; ++n) { const int idx = ((ai * 2 + bj) * 4 + m) * 2 + n; f32x4 a = acc[ai][bj][m][n], sg;
; #pragma unroll
;                             for (int e = 0; e < 4; ++e) sg[e] = __builtin_amdgcn_rcpf(1.0f + __builtin_amdgcn_exp2f((-1.4426950408889634f / 32.0f) * a[e]));
;                             tg[idx * 64] = pk4(sg); if (n) asm volatile("" ::: "memory"); }
	flat_store_dwordx2 v[134:135], v[96:97] offset:3584
	v_rcp_f32_e32 v96, v88
	v_pk_mul_f32 v[84:85], v[84:85], s[98:99] op_sel_hi:[1,0]
	s_movk_i32 s8, 0x1000
	v_exp_f32_e32 v84, v84
	v_exp_f32_e32 v85, v85
	v_add_co_u32_e32 v88, vcc, s8, v134
	v_cvt_pk_bf16_f32 v90, v94, v91
	s_nop 0
	v_addc_co_u32_e32 v89, vcc, 0, v135, vcc
	v_cvt_pk_bf16_f32 v91, v95, v96
	v_mul_f32_e32 v80, 0xbd38aa3b, v80
	flat_store_dwordx2 v[88:89], v[90:91] offset:512
	v_exp_f32_e32 v90, v80
	v_mul_f32_e32 v80, 0xbd38aa3b, v81
	v_pk_add_f32 v[84:85], v[84:85], s[100:101] op_sel_hi:[1,0]
	v_pk_mul_f32 v[86:87], v[86:87], s[98:99] op_sel_hi:[1,0]
	v_exp_f32_e32 v81, v80
	v_mul_f32_e32 v82, 0xbd38aa3b, v82
	v_rcp_f32_e32 v84, v84
	v_exp_f32_e32 v86, v86
	v_exp_f32_e32 v87, v87
	v_rcp_f32_e32 v85, v85
	v_exp_f32_e32 v82, v82
	v_mul_f32_e32 v83, 0xbd38aa3b, v83
	v_exp_f32_e32 v83, v83
	v_add_f32_e32 v81, 1.0, v81
	v_pk_add_f32 v[86:87], v[86:87], s[100:101] op_sel_hi:[1,0]
	v_cvt_pk_bf16_f32 v80, v84, v85
	v_rcp_f32_e32 v85, v81
	v_add_f32_e32 v81, 1.0, v82
	v_rcp_f32_e32 v86, v86
	v_rcp_f32_e32 v87, v87
	v_add_f32_e32 v84, 1.0, v90
	v_rcp_f32_e32 v82, v81
	v_add_f32_e32 v81, 1.0, v83
	v_rcp_f32_e32 v84, v84
	v_rcp_f32_e32 v83, v81
	v_pk_mul_f32 v[76:77], v[76:77], s[98:99] op_sel_hi:[1,0]
	v_exp_f32_e32 v76, v76
	v_exp_f32_e32 v77, v77
	flat_store_dwordx2 v[88:89], v[92:93]
	v_cvt_pk_bf16_f32 v81, v86, v87
	flat_store_dwordx2 v[88:89], v[80:81] offset:1024
	v_cvt_pk_bf16_f32 v80, v84, v85
	v_cvt_pk_bf16_f32 v81, v82, v83
	v_mul_f32_e32 v72, 0xbd38aa3b, v72
	flat_store_dwordx2 v[88:89], v[80:81] offset:1536
	v_exp_f32_e32 v80, v72
	v_mul_f32_e32 v72, 0xbd38aa3b, v73
	v_pk_add_f32 v[76:77], v[76:77], s[100:101] op_sel_hi:[1,0]
	v_pk_mul_f32 v[78:79], v[78:79], s[98:99] op_sel_hi:[1,0]
	v_exp_f32_e32 v73, v72
	v_mul_f32_e32 v74, 0xbd38aa3b, v74
	v_rcp_f32_e32 v76, v76
	v_exp_f32_e32 v78, v78
	v_exp_f32_e32 v79, v79
	v_rcp_f32_e32 v77, v77
	v_exp_f32_e32 v74, v74
	v_mul_f32_e32 v75, 0xbd38aa3b, v75
	v_exp_f32_e32 v75, v75
	v_add_f32_e32 v73, 1.0, v73
	v_pk_add_f32 v[78:79], v[78:79], s[100:101] op_sel_hi:[1,0]
	v_cvt_pk_bf16_f32 v72, v76, v77
	v_rcp_f32_e32 v77, v73
	v_add_f32_e32 v73, 1.0, v74
	v_rcp_f32_e32 v78, v78
	v_rcp_f32_e32 v79, v79
	v_add_f32_e32 v76, 1.0, v80
	v_rcp_f32_e32 v74, v73
	v_add_f32_e32 v73, 1.0, v75
	v_rcp_f32_e32 v76, v76
	v_rcp_f32_e32 v75, v73
	v_pk_mul_f32 v[68:69], v[68:69], s[98:99] op_sel_hi:[1,0]
	v_pk_mul_f32 v[60:61], v[60:61], s[98:99] op_sel_hi:[1,0]
	v_pk_mul_f32 v[62:63], v[62:63], s[98:99] op_sel_hi:[1,0]
	v_exp_f32_e32 v68, v68
	v_exp_f32_e32 v69, v69
	v_exp_f32_e32 v60, v60
	v_exp_f32_e32 v61, v61
	v_exp_f32_e32 v62, v62
	v_exp_f32_e32 v63, v63
	v_cvt_pk_bf16_f32 v73, v78, v79
	flat_store_dwordx2 v[88:89], v[72:73] offset:2048
	v_cvt_pk_bf16_f32 v72, v76, v77
	v_cvt_pk_bf16_f32 v73, v74, v75
	v_mul_f32_e32 v64, 0xbd38aa3b, v64
	flat_store_dwordx2 v[88:89], v[72:73] offset:2560
	v_exp_f32_e32 v72, v64
	v_mul_f32_e32 v64, 0xbd38aa3b, v65
	v_mul_f32_e32 v56, 0xbd38aa3b, v56
	v_pk_add_f32 v[68:69], v[68:69], s[100:101] op_sel_hi:[1,0]
	v_pk_mul_f32 v[70:71], v[70:71], s[98:99] op_sel_hi:[1,0]
	v_exp_f32_e32 v65, v64
	v_mul_f32_e32 v66, 0xbd38aa3b, v66
	v_pk_add_f32 v[60:61], v[60:61], s[100:101] op_sel_hi:[1,0]
	v_pk_add_f32 v[62:63], v[62:63], s[100:101] op_sel_hi:[1,0]
	v_exp_f32_e32 v56, v56
	v_mul_f32_e32 v57, 0xbd38aa3b, v57
	v_rcp_f32_e32 v68, v68
	v_exp_f32_e32 v70, v70
	v_exp_f32_e32 v71, v71
	v_rcp_f32_e32 v69, v69
	v_exp_f32_e32 v66, v66
	v_mul_f32_e32 v67, 0xbd38aa3b, v67
	v_rcp_f32_e32 v60, v60
	v_rcp_f32_e32 v61, v61
	v_rcp_f32_e32 v62, v62
	v_rcp_f32_e32 v63, v63
	v_exp_f32_e32 v57, v57
	v_exp_f32_e32 v67, v67
	v_add_f32_e32 v65, 1.0, v65
	v_add_f32_e32 v56, 1.0, v56
	v_pk_add_f32 v[70:71], v[70:71], s[100:101] op_sel_hi:[1,0]
	v_cvt_pk_bf16_f32 v64, v68, v69
	v_rcp_f32_e32 v69, v65
	v_add_f32_e32 v65, 1.0, v66
	v_cvt_pk_bf16_f32 v60, v60, v61
	v_cvt_pk_bf16_f32 v61, v62, v63
	v_rcp_f32_e32 v62, v56
	v_add_f32_e32 v56, 1.0, v57
	v_mul_f32_e32 v57, 0xbd38aa3b, v58
	v_rcp_f32_e32 v70, v70
	v_rcp_f32_e32 v71, v71
	v_add_f32_e32 v68, 1.0, v72
	v_rcp_f32_e32 v66, v65
	v_add_f32_e32 v65, 1.0, v67
	v_exp_f32_e32 v57, v57
	v_mul_f32_e32 v58, 0xbd38aa3b, v59
	v_rcp_f32_e32 v68, v68
	v_rcp_f32_e32 v67, v65
	v_exp_f32_e32 v58, v58
	v_cvt_pk_bf16_f32 v65, v70, v71
	v_rcp_f32_e32 v59, v56
	v_add_f32_e32 v56, 1.0, v57
	flat_store_dwordx2 v[88:89], v[64:65] offset:3072
	v_cvt_pk_bf16_f32 v64, v68, v69
	v_cvt_pk_bf16_f32 v65, v66, v67
	v_rcp_f32_e32 v63, v56
	v_add_f32_e32 v56, 1.0, v58
	flat_store_dwordx2 v[88:89], v[64:65] offset:3584
	v_rcp_f32_e32 v64, v56
	v_pk_mul_f32 v[52:53], v[52:53], s[98:99] op_sel_hi:[1,0]
	s_movk_i32 s8, 0x2000
	v_exp_f32_e32 v52, v52
	v_exp_f32_e32 v53, v53
	v_add_co_u32_e32 v56, vcc, s8, v134
	v_cvt_pk_bf16_f32 v58, v62, v59
	s_nop 0
	v_addc_co_u32_e32 v57, vcc, 0, v135, vcc
	v_cvt_pk_bf16_f32 v59, v63, v64
	v_mul_f32_e32 v48, 0xbd38aa3b, v48
	flat_store_dwordx2 v[56:57], v[58:59] offset:512
	v_exp_f32_e32 v58, v48
	v_mul_f32_e32 v48, 0xbd38aa3b, v49
	v_pk_add_f32 v[52:53], v[52:53], s[100:101] op_sel_hi:[1,0]
	v_pk_mul_f32 v[54:55], v[54:55], s[98:99] op_sel_hi:[1,0]
	v_exp_f32_e32 v49, v48
	v_mul_f32_e32 v50, 0xbd38aa3b, v50
	v_rcp_f32_e32 v52, v52
	v_exp_f32_e32 v54, v54
	v_exp_f32_e32 v55, v55
	v_rcp_f32_e32 v53, v53
	v_exp_f32_e32 v50, v50
	v_mul_f32_e32 v51, 0xbd38aa3b, v51
	v_exp_f32_e32 v51, v51
	v_add_f32_e32 v49, 1.0, v49
	v_pk_add_f32 v[54:55], v[54:55], s[100:101] op_sel_hi:[1,0]
	v_cvt_pk_bf16_f32 v48, v52, v53
	v_rcp_f32_e32 v53, v49
	v_add_f32_e32 v49, 1.0, v50
	v_rcp_f32_e32 v54, v54
; __device__ __forceinline__ u32x2 pk4(f32x4 v) { u32x2 w; w.x = pk2(v[0], v[1]); w.y = pk2(v[2], v[3]); return w; }
;     __device__ __forceinline__ void operator()(const f32x4 (&acc)[2][2][4][2], const Unit& u, int wr, int wc, int fr, int fq) const {
;     ...
;         if (mode == 0) {
; #pragma unroll
;             for (int ai = 0; ai < 2; ++ai)
; #pragma unroll
;                 for (int bj = 0; bj < 2; ++bj)
; #pragma unroll
;                     for (int m = 0; m < 4; ++m)
; #pragma unroll
;                         for (int n = 0; n < 2; ++n) { const int idx = ((ai * 2 + bj) * 4 + m) * 2 + n; f32x4 a = acc[ai][bj][m][n], sg;
; #pragma unroll
;                             for (int e = 0; e < 4; ++e) sg[e] = __builtin_amdgcn_rcpf(1.0f + __builtin_amdgcn_exp2f((-1.4426950408889634f / 32.0f) * a[e]));
;                             tg[idx * 64] = pk4(sg); if (n) asm volatile("" ::: "memory"); }
	v_rcp_f32_e32 v55, v55
	v_add_f32_e32 v52, 1.0, v58
	v_rcp_f32_e32 v50, v49
	v_add_f32_e32 v49, 1.0, v51
	v_rcp_f32_e32 v52, v52
	v_rcp_f32_e32 v51, v49
	v_pk_mul_f32 v[44:45], v[44:45], s[98:99] op_sel_hi:[1,0]
	v_exp_f32_e32 v44, v44
	v_exp_f32_e32 v45, v45
	flat_store_dwordx2 v[56:57], v[60:61]
	v_cvt_pk_bf16_f32 v49, v54, v55
	flat_store_dwordx2 v[56:57], v[48:49] offset:1024
	v_cvt_pk_bf16_f32 v48, v52, v53
	v_cvt_pk_bf16_f32 v49, v50, v51
	v_mul_f32_e32 v40, 0xbd38aa3b, v40
	flat_store_dwordx2 v[56:57], v[48:49] offset:1536
	v_exp_f32_e32 v48, v40
	v_mul_f32_e32 v40, 0xbd38aa3b, v41
	v_pk_add_f32 v[44:45], v[44:45], s[100:101] op_sel_hi:[1,0]
	v_pk_mul_f32 v[46:47], v[46:47], s[98:99] op_sel_hi:[1,0]
	v_exp_f32_e32 v41, v40
	v_mul_f32_e32 v42, 0xbd38aa3b, v42
	v_rcp_f32_e32 v44, v44
	v_exp_f32_e32 v46, v46
	v_exp_f32_e32 v47, v47
	v_rcp_f32_e32 v45, v45
	v_exp_f32_e32 v42, v42
	v_mul_f32_e32 v43, 0xbd38aa3b, v43
	v_exp_f32_e32 v43, v43
	v_add_f32_e32 v41, 1.0, v41
	v_pk_add_f32 v[46:47], v[46:47], s[100:101] op_sel_hi:[1,0]
	v_cvt_pk_bf16_f32 v40, v44, v45
	v_rcp_f32_e32 v45, v41
	v_add_f32_e32 v41, 1.0, v42
	v_rcp_f32_e32 v46, v46
	v_rcp_f32_e32 v47, v47
	v_add_f32_e32 v44, 1.0, v48
	v_rcp_f32_e32 v42, v41
	v_add_f32_e32 v41, 1.0, v43
	v_rcp_f32_e32 v44, v44
	v_rcp_f32_e32 v43, v41
	v_pk_mul_f32 v[36:37], v[36:37], s[98:99] op_sel_hi:[1,0]
	v_pk_mul_f32 v[28:29], v[28:29], s[98:99] op_sel_hi:[1,0]
	v_pk_mul_f32 v[30:31], v[30:31], s[98:99] op_sel_hi:[1,0]
	v_exp_f32_e32 v36, v36
	v_exp_f32_e32 v37, v37
	v_exp_f32_e32 v28, v28
	v_exp_f32_e32 v29, v29
	v_exp_f32_e32 v30, v30
	v_exp_f32_e32 v31, v31
	v_cvt_pk_bf16_f32 v41, v46, v47
	flat_store_dwordx2 v[56:57], v[40:41] offset:2048
	v_cvt_pk_bf16_f32 v40, v44, v45
	v_cvt_pk_bf16_f32 v41, v42, v43
	v_mul_f32_e32 v32, 0xbd38aa3b, v32
	flat_store_dwordx2 v[56:57], v[40:41] offset:2560
	v_exp_f32_e32 v40, v32
	v_mul_f32_e32 v32, 0xbd38aa3b, v33
	v_mul_f32_e32 v24, 0xbd38aa3b, v24
	v_pk_add_f32 v[36:37], v[36:37], s[100:101] op_sel_hi:[1,0]
	v_pk_mul_f32 v[38:39], v[38:39], s[98:99] op_sel_hi:[1,0]
	v_exp_f32_e32 v33, v32
	v_mul_f32_e32 v34, 0xbd38aa3b, v34
	v_pk_add_f32 v[28:29], v[28:29], s[100:101] op_sel_hi:[1,0]
	v_pk_add_f32 v[30:31], v[30:31], s[100:101] op_sel_hi:[1,0]
	v_exp_f32_e32 v24, v24
	v_mul_f32_e32 v25, 0xbd38aa3b, v25
	v_rcp_f32_e32 v36, v36
	v_exp_f32_e32 v38, v38
	v_exp_f32_e32 v39, v39
	v_rcp_f32_e32 v37, v37
	v_exp_f32_e32 v34, v34
	v_mul_f32_e32 v35, 0xbd38aa3b, v35
	v_rcp_f32_e32 v28, v28
	v_rcp_f32_e32 v29, v29
	v_rcp_f32_e32 v30, v30
	v_rcp_f32_e32 v31, v31
	v_exp_f32_e32 v25, v25
	v_exp_f32_e32 v35, v35
	v_add_f32_e32 v33, 1.0, v33
	v_add_f32_e32 v24, 1.0, v24
	v_pk_add_f32 v[38:39], v[38:39], s[100:101] op_sel_hi:[1,0]
	v_cvt_pk_bf16_f32 v32, v36, v37
	v_rcp_f32_e32 v37, v33
	v_add_f32_e32 v33, 1.0, v34
	v_cvt_pk_bf16_f32 v28, v28, v29
	v_cvt_pk_bf16_f32 v29, v30, v31
	v_rcp_f32_e32 v30, v24
	v_add_f32_e32 v24, 1.0, v25
	v_mul_f32_e32 v25, 0xbd38aa3b, v26
	v_rcp_f32_e32 v38, v38
	v_rcp_f32_e32 v39, v39
	v_add_f32_e32 v36, 1.0, v40
	v_rcp_f32_e32 v34, v33
	v_add_f32_e32 v33, 1.0, v35
	v_exp_f32_e32 v25, v25
	v_mul_f32_e32 v26, 0xbd38aa3b, v27
	v_rcp_f32_e32 v36, v36
	v_rcp_f32_e32 v35, v33
	v_exp_f32_e32 v26, v26
	v_cvt_pk_bf16_f32 v33, v38, v39
	v_rcp_f32_e32 v27, v24
	v_add_f32_e32 v24, 1.0, v25
	flat_store_dwordx2 v[56:57], v[32:33] offset:3072
	v_cvt_pk_bf16_f32 v32, v36, v37
	v_cvt_pk_bf16_f32 v33, v34, v35
	v_rcp_f32_e32 v31, v24
	v_add_f32_e32 v24, 1.0, v26
	flat_store_dwordx2 v[56:57], v[32:33] offset:3584
; __device__ __forceinline__ u32x2 pk4(f32x4 v) { u32x2 w; w.x = pk2(v[0], v[1]); w.y = pk2(v[2], v[3]); return w; }
;     __device__ __forceinline__ void operator()(const f32x4 (&acc)[2][2][4][2], const Unit& u, int wr, int wc, int fr, int fq) const {
;     ...
;         if (mode == 0) {
; #pragma unroll
;             for (int ai = 0; ai < 2; ++ai)
; #pragma unroll
;                 for (int bj = 0; bj < 2; ++bj)
; #pragma unroll
;                     for (int m = 0; m < 4; ++m)
; #pragma unroll
;                         for (int n = 0; n < 2; ++n) { const int idx = ((ai * 2 + bj) * 4 + m) * 2 + n; f32x4 a = acc[ai][bj][m][n], sg;
; #pragma unroll
;                             for (int e = 0; e < 4; ++e) sg[e] = __builtin_amdgcn_rcpf(1.0f + __builtin_amdgcn_exp2f((-1.4426950408889634f / 32.0f) * a[e]));
;                             tg[idx * 64] = pk4(sg); if (n) asm volatile("" ::: "memory"); }
	v_rcp_f32_e32 v32, v24
	v_pk_mul_f32 v[20:21], v[20:21], s[98:99] op_sel_hi:[1,0]
	s_movk_i32 s8, 0x3000
	v_exp_f32_e32 v20, v20
	v_exp_f32_e32 v21, v21
	v_add_co_u32_e32 v24, vcc, s8, v134
	v_cvt_pk_bf16_f32 v26, v30, v27
	s_nop 0
	v_addc_co_u32_e32 v25, vcc, 0, v135, vcc
	v_cvt_pk_bf16_f32 v27, v31, v32
	v_mul_f32_e32 v16, 0xbd38aa3b, v16
	flat_store_dwordx2 v[24:25], v[26:27] offset:512
	v_exp_f32_e32 v26, v16
	v_mul_f32_e32 v16, 0xbd38aa3b, v17
	v_pk_add_f32 v[20:21], v[20:21], s[100:101] op_sel_hi:[1,0]
	v_pk_mul_f32 v[22:23], v[22:23], s[98:99] op_sel_hi:[1,0]
	v_exp_f32_e32 v17, v16
	v_mul_f32_e32 v18, 0xbd38aa3b, v18
	v_rcp_f32_e32 v20, v20
	v_exp_f32_e32 v22, v22
	v_exp_f32_e32 v23, v23
	v_rcp_f32_e32 v21, v21
	v_exp_f32_e32 v18, v18
	v_mul_f32_e32 v19, 0xbd38aa3b, v19
	v_exp_f32_e32 v19, v19
	v_add_f32_e32 v17, 1.0, v17
	v_pk_add_f32 v[22:23], v[22:23], s[100:101] op_sel_hi:[1,0]
	v_cvt_pk_bf16_f32 v16, v20, v21
	v_rcp_f32_e32 v21, v17
	v_add_f32_e32 v17, 1.0, v18
	v_rcp_f32_e32 v22, v22
	v_rcp_f32_e32 v23, v23
	v_add_f32_e32 v20, 1.0, v26
	v_rcp_f32_e32 v18, v17
	v_add_f32_e32 v17, 1.0, v19
	v_rcp_f32_e32 v20, v20
	v_rcp_f32_e32 v19, v17
	v_pk_mul_f32 v[12:13], v[12:13], s[98:99] op_sel_hi:[1,0]
	v_exp_f32_e32 v12, v12
	v_exp_f32_e32 v13, v13
	flat_store_dwordx2 v[24:25], v[28:29]
	v_cvt_pk_bf16_f32 v17, v22, v23
	flat_store_dwordx2 v[24:25], v[16:17] offset:1024
	v_cvt_pk_bf16_f32 v16, v20, v21
	v_cvt_pk_bf16_f32 v17, v18, v19
	v_mul_f32_e32 v8, 0xbd38aa3b, v8
	flat_store_dwordx2 v[24:25], v[16:17] offset:1536
	v_exp_f32_e32 v16, v8
	v_mul_f32_e32 v8, 0xbd38aa3b, v9
	v_pk_add_f32 v[12:13], v[12:13], s[100:101] op_sel_hi:[1,0]
	v_pk_mul_f32 v[14:15], v[14:15], s[98:99] op_sel_hi:[1,0]
	v_exp_f32_e32 v9, v8
	v_mul_f32_e32 v10, 0xbd38aa3b, v10
	v_rcp_f32_e32 v12, v12
	v_exp_f32_e32 v14, v14
	v_exp_f32_e32 v15, v15
	v_rcp_f32_e32 v13, v13
	v_exp_f32_e32 v10, v10
	v_mul_f32_e32 v11, 0xbd38aa3b, v11
	v_exp_f32_e32 v11, v11
	v_add_f32_e32 v9, 1.0, v9
	v_pk_add_f32 v[14:15], v[14:15], s[100:101] op_sel_hi:[1,0]
	v_cvt_pk_bf16_f32 v8, v12, v13
	v_rcp_f32_e32 v13, v9
	v_add_f32_e32 v9, 1.0, v10
	v_rcp_f32_e32 v14, v14
	v_rcp_f32_e32 v15, v15
	v_add_f32_e32 v12, 1.0, v16
	v_rcp_f32_e32 v10, v9
	v_add_f32_e32 v9, 1.0, v11
	v_rcp_f32_e32 v12, v12
	v_rcp_f32_e32 v11, v9
	v_pk_mul_f32 v[4:5], v[4:5], s[98:99] op_sel_hi:[1,0]
	v_exp_f32_e32 v4, v4
	v_exp_f32_e32 v5, v5
	v_cvt_pk_bf16_f32 v9, v14, v15
	flat_store_dwordx2 v[24:25], v[8:9] offset:2048
	v_cvt_pk_bf16_f32 v8, v12, v13
	v_cvt_pk_bf16_f32 v9, v10, v11
	v_mul_f32_e32 v0, 0xbd38aa3b, v0
	flat_store_dwordx2 v[24:25], v[8:9] offset:2560
	v_exp_f32_e32 v8, v0
	v_mul_f32_e32 v0, 0xbd38aa3b, v1
	v_pk_add_f32 v[4:5], v[4:5], s[100:101] op_sel_hi:[1,0]
	v_pk_mul_f32 v[6:7], v[6:7], s[98:99] op_sel_hi:[1,0]
	v_exp_f32_e32 v1, v0
	v_mul_f32_e32 v2, 0xbd38aa3b, v2
	v_rcp_f32_e32 v4, v4
	v_exp_f32_e32 v6, v6
	v_exp_f32_e32 v7, v7
	v_rcp_f32_e32 v5, v5
	v_exp_f32_e32 v2, v2
	v_mul_f32_e32 v3, 0xbd38aa3b, v3
	v_exp_f32_e32 v3, v3
	v_add_f32_e32 v1, 1.0, v1
	v_pk_add_f32 v[6:7], v[6:7], s[100:101] op_sel_hi:[1,0]
	v_cvt_pk_bf16_f32 v0, v4, v5
	v_rcp_f32_e32 v5, v1
	v_add_f32_e32 v1, 1.0, v2
	v_rcp_f32_e32 v6, v6
	v_rcp_f32_e32 v7, v7
	v_add_f32_e32 v4, 1.0, v8
	v_rcp_f32_e32 v2, v1
	v_add_f32_e32 v1, 1.0, v3
	v_rcp_f32_e32 v4, v4
	v_rcp_f32_e32 v3, v1
	v_cvt_pk_bf16_f32 v1, v6, v7
	flat_store_dwordx2 v[24:25], v[0:1] offset:3072
	v_cvt_pk_bf16_f32 v0, v4, v5
	v_cvt_pk_bf16_f32 v1, v2, v3
	flat_store_dwordx2 v[24:25], v[0:1] offset:3584
